# v30 plus counted vmcnt at the LRU chunk loop head and permlane-swap max reduction in attention
# baseline (speedup 1.0000x reference)
; __device__ __forceinline__ void phase_lru(const Params& p, LAS unsigned char* lds) {
;     ...
;             const float ba = p.in[19][d * D + ch], bi = p.in[21][d * D + ch];
;             const float lam = p.in[22][d * D + ch];
;             const float c8 = -8.0f * log1pf(expf(-lam));
;             const float nba = -1.4426950408889634f * ba, nbi = -1.4426950408889634f * bi, c8l = 1.4426950408889634f * c8;
.LBB0_573:
	s_or_b64 exec, exec, s[4:5]
	s_waitcnt vmcnt(0)
	v_mul_f32_e32 v1, 0xbfb8aa3b, v110
	v_rndne_f32_e32 v2, v1
	v_sub_f32_e32 v3, v1, v2
	v_fma_f32 v1, v110, s56, -v1
	v_fmac_f32_e32 v1, 0xb2a5705f, v110
	v_add_f32_e32 v1, v3, v1
	v_exp_f32_e32 v1, v1
	v_cvt_i32_f32_e32 v2, v2
	v_cmp_nlt_f32_e32 vcc, s57, v110
	s_xor_b64 s[54:55], s[52:53], -1
	s_mov_b32 s10, 1
	v_ldexp_f32 v1, v1, v2
	v_cndmask_b32_e32 v1, 0, v1, vcc
	v_cmp_ngt_f32_e32 vcc, s58, v110
	v_mul_f32_e32 v197, 0xbfb8aa3b, v109
	v_mul_f32_e32 v198, 0xbfb8aa3b, v108
	v_cndmask_b32_e32 v1, v194, v1, vcc
	v_add_f32_e32 v110, 1.0, v1
	v_add_f32_e32 v2, -1.0, v110
	v_sub_f32_e32 v3, v2, v110
	v_add_f32_e32 v3, 1.0, v3
	v_sub_f32_e32 v2, v1, v2
	v_add_f32_e32 v111, v2, v3
	v_frexp_mant_f32_e32 v112, v110
	v_cvt_f64_f32_e32 v[2:3], v110
	v_frexp_exp_i32_f64_e32 v2, v[2:3]
	v_cmp_gt_f32_e32 vcc, s60, v112
	s_xor_b64 s[6:7], s[0:1], s[52:53]
	s_mov_b32 s88, s80
	v_subbrev_co_u32_e32 v2, vcc, 0, v2, vcc
	v_sub_u32_e32 v3, 0, v2
	v_ldexp_f32 v110, v110, v3
	v_ldexp_f32 v3, v111, v3
	v_add_f32_e32 v111, -1.0, v110
	v_add_f32_e32 v114, 1.0, v110
	v_add_f32_e32 v112, 1.0, v111
	v_add_f32_e32 v115, -1.0, v114
	v_sub_f32_e32 v112, v110, v112
	v_sub_f32_e32 v110, v110, v115
	v_add_f32_e32 v112, v3, v112
	v_add_f32_e32 v3, v3, v110
	v_add_f32_e32 v110, v114, v3
	v_rcp_f32_e32 v115, v110
	v_add_f32_e32 v113, v111, v112
	v_sub_f32_e32 v111, v111, v113
	v_add_f32_e32 v111, v112, v111
	v_sub_f32_e32 v112, v114, v110
	v_add_f32_e32 v3, v3, v112
	v_mul_f32_e32 v112, v113, v115
	v_mul_f32_e32 v114, v110, v112
	v_fma_f32 v161, v112, v110, -v114
	v_fmac_f32_e32 v161, v112, v3
	v_add_f32_e32 v162, v114, v161
	v_sub_f32_e32 v163, v113, v162
	v_sub_f32_e32 v113, v113, v163
	v_sub_f32_e32 v114, v162, v114
	v_sub_f32_e32 v113, v113, v162
	v_add_f32_e32 v111, v111, v113
	v_sub_f32_e32 v113, v114, v161
	v_add_f32_e32 v111, v113, v111
	v_add_f32_e32 v113, v163, v111
	v_mul_f32_e32 v114, v115, v113
	v_mul_f32_e32 v161, v110, v114
	v_fma_f32 v110, v114, v110, -v161
	v_fmac_f32_e32 v110, v114, v3
	v_sub_f32_e32 v3, v163, v113
	v_add_f32_e32 v3, v111, v3
	v_add_f32_e32 v111, v161, v110
	v_sub_f32_e32 v162, v113, v111
	v_sub_f32_e32 v113, v113, v162
	v_sub_f32_e32 v161, v111, v161
	v_sub_f32_e32 v111, v113, v111
	v_add_f32_e32 v3, v3, v111
	v_sub_f32_e32 v110, v161, v110
	v_cvt_f32_i32_e32 v2, v2
	v_add_f32_e32 v3, v110, v3
	v_add_f32_e32 v110, v112, v114
	v_add_f32_e32 v3, v162, v3
	v_sub_f32_e32 v111, v110, v112
	v_mul_f32_e32 v3, v115, v3
	v_sub_f32_e32 v111, v114, v111
	v_add_f32_e32 v3, v111, v3
	v_mul_f32_e32 v114, 0x3f317218, v2
	v_add_f32_e32 v111, v110, v3
	v_fma_f32 v115, v2, s61, -v114
	v_mul_f32_e32 v112, v111, v111
	v_fmac_f32_e32 v115, 0xb102e308, v2
	v_sub_f32_e32 v2, v111, v110
	v_fmamk_f32 v113, v112, 0x3e9b6dac, v190
	v_sub_f32_e32 v2, v3, v2
	v_add_f32_e32 v3, v114, v115
	v_fmaak_f32 v113, v112, v113, 0x3f2aaada
	v_sub_f32_e32 v110, v3, v114
	v_ldexp_f32 v114, v111, 1
	v_mul_f32_e32 v111, v111, v112
	v_mul_f32_e32 v111, v111, v113
	v_add_f32_e32 v112, v114, v111
	v_sub_f32_e32 v113, v112, v114
	v_ldexp_f32 v2, v2, 1
	v_sub_f32_e32 v111, v111, v113
	v_add_f32_e32 v2, v2, v111
	v_add_f32_e32 v111, v112, v2
	v_sub_f32_e32 v112, v111, v112
	v_sub_f32_e32 v2, v2, v112
	v_add_f32_e32 v112, v3, v111
	v_sub_f32_e32 v113, v112, v3
	v_sub_f32_e32 v114, v112, v113
	v_sub_f32_e32 v110, v115, v110
	v_sub_f32_e32 v3, v3, v114
	v_sub_f32_e32 v111, v111, v113
	v_add_f32_e32 v3, v111, v3
	v_add_f32_e32 v111, v110, v2
	v_sub_f32_e32 v113, v111, v110
	v_sub_f32_e32 v114, v111, v113
	v_sub_f32_e32 v110, v110, v114
	v_sub_f32_e32 v2, v2, v113
	v_add_f32_e32 v3, v111, v3
	v_add_f32_e32 v2, v2, v110
	v_add_f32_e32 v110, v112, v3
	v_sub_f32_e32 v111, v110, v112
	v_sub_f32_e32 v3, v3, v111
	v_add_f32_e32 v2, v2, v3
	v_add_f32_e32 v2, v110, v2
	v_cmp_neq_f32_e32 vcc, s59, v1
	s_nop 1
	v_cndmask_b32_e32 v2, v194, v2, vcc
	v_cmp_lt_f32_e64 vcc, |v1|, s62
	s_nop 1
	v_cndmask_b32_e32 v1, v2, v1, vcc
	v_mul_f32_e32 v1, 0xc1000000, v1
	v_cndmask_b32_e64 v2, v187, v188, s[52:53]
	v_cmp_eq_u32_e64 s[4:5], 0, v2
	v_mul_f32_e32 v199, 0x3fb8aa3b, v1
	s_waitcnt vmcnt(0)
; #define LAS __attribute__((address_space(3)))
; __device__ __forceinline__ unsigned pk_bf16(float lo, float hi) { const f32x2 v = {lo, hi}; const bf16x2_t b = __builtin_convertvector(v, bf16x2_t); return __builtin_bit_cast(unsigned, b); }
; __device__ __forceinline__ float lo_bf(unsigned w) { return __uint_as_float(w << 16); }
; __device__ __forceinline__ float hi_bf(unsigned w) { return __uint_as_float(w & 0xffff0000u); }
; #define LRU_PREFETCH(CI) do { const int _cc = d ? (nch - 1 - (CI)) : (CI); _Pragma("unroll") for (int hf = 0; hf < 2; ++hf) _Pragma("unroll") for (int j = 0; j < 4; ++j) { \
;                 const int tt = _cc * 64 + tr + 32 * hf + j - 1; pw[hf][j] = (tt >= 0 && tt < S) ? *(const u32x4*)(XL + (size_t)(row0 + tt) * D + c0) : (u32x4){0u, 0u, 0u, 0u}; } } while (0)
; __device__ __forceinline__ void phase_lru(const Params& p, LAS unsigned char* lds) {
;     ...
;             for (int ci = 0; ci < nch; ++ci) {
;                 const int cc = d ? (nch - 1 - ci) : ci, t0 = cc * 64;
;                 __syncthreads();
; #pragma unroll
;                 for (int hf = 0; hf < 2; ++hf) {
;                     const int tl = tr + 32 * hf;
;                     float a[8];
; #pragma unroll
;                     for (int e = 0; e < 8; ++e) a[e] = cb[e];
; #pragma unroll
;                     for (int j = 0; j < 4; ++j) { const u32x4 w = pw[hf][j];
;                         a[0] += cw[j][0] * lo_bf(w.x); a[1] += cw[j][1] * hi_bf(w.x); a[2] += cw[j][2] * lo_bf(w.y); a[3] += cw[j][3] * hi_bf(w.y);
;                         a[4] += cw[j][4] * lo_bf(w.z); a[5] += cw[j][5] * hi_bf(w.z); a[6] += cw[j][6] * lo_bf(w.w); a[7] += cw[j][7] * hi_bf(w.w); }
;                     u32x4 o; o.x = pk_bf16(a[0], a[1]); o.y = pk_bf16(a[2], a[3]); o.z = pk_bf16(a[4], a[5]); o.w = pk_bf16(a[6], a[7]);
;                     *(LAS u32x4*)(lds + tl * XC_PITCH + cgp * 2) = o;
;                 }
;                 __syncthreads();
;                 if (ci + 1 < nch) LRU_PREFETCH(ci + 1);
.LBB0_574:
	s_waitcnt vmcnt(16)
	v_lshlrev_b32_e32 v2, 16, v76
	v_and_b32_e32 v3, 0xffff0000, v76
	v_pk_fma_f32 v[2:3], v[28:29], v[2:3], v[32:33]
	v_lshlrev_b32_e32 v108, 16, v80
	v_and_b32_e32 v109, 0xffff0000, v80
	v_pk_fma_f32 v[2:3], v[4:5], v[108:109], v[2:3]
	v_lshlrev_b32_e32 v108, 16, v84
	v_and_b32_e32 v109, 0xffff0000, v84
	v_pk_fma_f32 v[2:3], v[8:9], v[108:109], v[2:3]
	v_lshlrev_b32_e32 v108, 16, v88
	v_and_b32_e32 v109, 0xffff0000, v88
	v_pk_fma_f32 v[2:3], v[20:21], v[108:109], v[2:3]
	v_lshlrev_b32_e32 v108, 16, v77
	v_and_b32_e32 v109, 0xffff0000, v77
	v_pk_fma_f32 v[108:109], v[30:31], v[108:109], v[34:35]
	v_lshlrev_b32_e32 v110, 16, v81
	v_and_b32_e32 v111, 0xffff0000, v81
	v_pk_fma_f32 v[108:109], v[6:7], v[110:111], v[108:109]
	v_lshlrev_b32_e32 v110, 16, v85
	v_and_b32_e32 v111, 0xffff0000, v85
	v_pk_fma_f32 v[108:109], v[10:11], v[110:111], v[108:109]
	v_lshlrev_b32_e32 v110, 16, v89
	v_and_b32_e32 v111, 0xffff0000, v89
	v_pk_fma_f32 v[110:111], v[22:23], v[110:111], v[108:109]
	v_lshlrev_b32_e32 v108, 16, v78
	v_and_b32_e32 v109, 0xffff0000, v78
	v_pk_fma_f32 v[108:109], v[36:37], v[108:109], v[40:41]
	v_lshlrev_b32_e32 v112, 16, v82
	v_and_b32_e32 v113, 0xffff0000, v82
	v_pk_fma_f32 v[108:109], v[12:13], v[112:113], v[108:109]
	v_lshlrev_b32_e32 v112, 16, v86
	v_and_b32_e32 v113, 0xffff0000, v86
	v_pk_fma_f32 v[108:109], v[16:17], v[112:113], v[108:109]
	v_lshlrev_b32_e32 v112, 16, v90
	v_and_b32_e32 v113, 0xffff0000, v90
	v_pk_fma_f32 v[112:113], v[24:25], v[112:113], v[108:109]
	v_lshlrev_b32_e32 v108, 16, v79
	v_and_b32_e32 v109, 0xffff0000, v79
	v_pk_fma_f32 v[108:109], v[38:39], v[108:109], v[42:43]
	v_lshlrev_b32_e32 v114, 16, v83
	v_and_b32_e32 v115, 0xffff0000, v83
	v_pk_fma_f32 v[108:109], v[14:15], v[114:115], v[108:109]
	v_lshlrev_b32_e32 v114, 16, v87
	v_and_b32_e32 v115, 0xffff0000, v87
	v_pk_fma_f32 v[108:109], v[18:19], v[114:115], v[108:109]
	v_lshlrev_b32_e32 v114, 16, v91
	v_and_b32_e32 v115, 0xffff0000, v91
	v_pk_fma_f32 v[114:115], v[26:27], v[114:115], v[108:109]
	v_cvt_pk_bf16_f32 v108, v2, v3
	v_cvt_pk_bf16_f32 v109, v110, v111
	v_cvt_pk_bf16_f32 v110, v112, v113
	v_cvt_pk_bf16_f32 v111, v114, v115
	v_lshlrev_b32_e32 v2, 16, v92
	v_and_b32_e32 v3, 0xffff0000, v92
	s_barrier
	ds_write_b128 v191, v[108:111]
	v_pk_fma_f32 v[2:3], v[28:29], v[2:3], v[32:33]
	v_lshlrev_b32_e32 v108, 16, v96
	v_and_b32_e32 v109, 0xffff0000, v96
	v_pk_fma_f32 v[2:3], v[4:5], v[108:109], v[2:3]
	v_lshlrev_b32_e32 v108, 16, v100
	v_and_b32_e32 v109, 0xffff0000, v100
	v_pk_fma_f32 v[2:3], v[8:9], v[108:109], v[2:3]
	v_lshlrev_b32_e32 v108, 16, v104
	v_and_b32_e32 v109, 0xffff0000, v104
	v_pk_fma_f32 v[2:3], v[20:21], v[108:109], v[2:3]
	v_lshlrev_b32_e32 v108, 16, v93
	v_and_b32_e32 v109, 0xffff0000, v93
	v_pk_fma_f32 v[108:109], v[30:31], v[108:109], v[34:35]
	v_lshlrev_b32_e32 v110, 16, v97
	v_and_b32_e32 v111, 0xffff0000, v97
	v_pk_fma_f32 v[108:109], v[6:7], v[110:111], v[108:109]
	v_lshlrev_b32_e32 v110, 16, v101
	v_and_b32_e32 v111, 0xffff0000, v101
	v_pk_fma_f32 v[108:109], v[10:11], v[110:111], v[108:109]
	v_lshlrev_b32_e32 v110, 16, v105
	v_and_b32_e32 v111, 0xffff0000, v105
	v_pk_fma_f32 v[110:111], v[22:23], v[110:111], v[108:109]
	v_lshlrev_b32_e32 v108, 16, v94
	v_and_b32_e32 v109, 0xffff0000, v94
	v_pk_fma_f32 v[108:109], v[36:37], v[108:109], v[40:41]
	v_lshlrev_b32_e32 v112, 16, v98
	v_and_b32_e32 v113, 0xffff0000, v98
	v_pk_fma_f32 v[108:109], v[12:13], v[112:113], v[108:109]
	v_lshlrev_b32_e32 v112, 16, v102
	v_and_b32_e32 v113, 0xffff0000, v102
	v_pk_fma_f32 v[108:109], v[16:17], v[112:113], v[108:109]
	v_lshlrev_b32_e32 v112, 16, v106
	v_and_b32_e32 v113, 0xffff0000, v106
	v_pk_fma_f32 v[112:113], v[24:25], v[112:113], v[108:109]
	v_lshlrev_b32_e32 v108, 16, v95
	v_and_b32_e32 v109, 0xffff0000, v95
	v_pk_fma_f32 v[108:109], v[38:39], v[108:109], v[42:43]
	v_lshlrev_b32_e32 v114, 16, v99
	v_and_b32_e32 v115, 0xffff0000, v99
	v_pk_fma_f32 v[108:109], v[14:15], v[114:115], v[108:109]
	v_lshlrev_b32_e32 v114, 16, v103
	v_and_b32_e32 v115, 0xffff0000, v103
	v_pk_fma_f32 v[108:109], v[18:19], v[114:115], v[108:109]
	v_lshlrev_b32_e32 v114, 16, v107
	v_and_b32_e32 v115, 0xffff0000, v107
	v_pk_fma_f32 v[114:115], v[26:27], v[114:115], v[108:109]
	v_cvt_pk_bf16_f32 v108, v2, v3
	v_cvt_pk_bf16_f32 v109, v110, v111
	v_cvt_pk_bf16_f32 v110, v112, v113
	v_cvt_pk_bf16_f32 v111, v114, v115
	s_cmp_ge_u32 s10, s79
	ds_write_b128 v191, v[108:111] offset:8704
	s_waitcnt lgkmcnt(0)
	s_barrier
	s_cbranch_scc1 .LBB0_592
	s_add_i32 s33, s88, -1
	s_and_b64 s[8:9], s[52:53], exec
	s_cselect_b32 s33, s10, s33
	s_cmp_lt_i32 s33, 1
	s_cbranch_scc1 .Llru_pf_slow
	s_lshr_b32 s32, s78, 6
	s_add_i32 s32, s32, -1
	s_cmp_ge_i32 s33, s32
	s_cbranch_scc1 .Llru_pf_slow
	v_lshl_or_b32 v1, s33, 6, v184
	v_add_u32_e32 v2, s77, v1
	v_add_u32_e32 v2, 1, v2
	v_ashrrev_i32_e32 v3, 31, v2
	v_lshlrev_b64 v[2:3], 11, v[2:3]
	v_lshl_add_u64 v[2:3], v[120:121], 0, v[2:3]
	s_mov_b64 s[68:69], 0x10000
	v_lshl_add_u64 v[108:109], v[2:3], 0, s[68:69]
	global_load_dwordx4 v[76:79], v[2:3], off offset:-4096
	global_load_dwordx4 v[80:83], v[2:3], off offset:-2048
	global_load_dwordx4 v[84:87], v[2:3], off
	global_load_dwordx4 v[88:91], v[2:3], off offset:2048
	global_load_dwordx4 v[92:95], v[108:109], off offset:-4096
	global_load_dwordx4 v[96:99], v[108:109], off offset:-2048
	global_load_dwordx4 v[100:103], v[108:109], off
	global_load_dwordx4 v[104:107], v[108:109], off offset:2048
	s_branch .LBB0_592

.LBB0_732:
	ds_read_b128 v[110:113], v182
	ds_read_b128 v[122:125], v182 offset:64
	ds_read_b128 v[118:121], v182 offset:3328
	ds_read_b128 v[136:139], v182 offset:128
	ds_read_b128 v[140:143], v182 offset:6656
	ds_read_b128 v[148:151], v182 offset:6720
	ds_read_b128 v[152:155], v182 offset:9984
	ds_read_b128 v[156:159], v182 offset:6784
	s_waitcnt lgkmcnt(7)
	v_mfma_f32_16x16x32_bf16 v[114:117], v[110:113], v[0:3], 0
	ds_read_b128 v[164:167], v182 offset:3392
	ds_read_b128 v[186:189], v182 offset:3456
	ds_read_b128 v[190:193], v182 offset:10048
	ds_read_b128 v[194:197], v182 offset:10112
	s_add_i32 s28, s31, -3
	s_waitcnt lgkmcnt(9)
	v_mfma_f32_16x16x32_bf16 v[130:133], v[118:121], v[0:3], 0
	s_cmp_ge_u32 s28, s30
	v_mfma_f32_16x16x32_bf16 v[114:117], v[122:125], v[4:7], v[114:117]
	s_waitcnt lgkmcnt(7)
	v_mfma_f32_16x16x32_bf16 v[144:147], v[140:143], v[0:3], 0
	s_waitcnt lgkmcnt(5)
	v_mfma_f32_16x16x32_bf16 v[160:163], v[152:155], v[0:3], 0
	s_waitcnt lgkmcnt(3)
	v_mfma_f32_16x16x32_bf16 v[130:133], v[164:167], v[4:7], v[130:133]
	v_mfma_f32_16x16x32_bf16 v[114:117], v[136:139], v[16:19], v[114:117]
	v_mfma_f32_16x16x32_bf16 v[144:147], v[148:151], v[4:7], v[144:147]
	s_waitcnt lgkmcnt(1)
	v_mfma_f32_16x16x32_bf16 v[160:163], v[190:193], v[4:7], v[160:163]
	s_nop 4
	v_max_f32_e32 v80, v114, v115
	s_nop 0
	s_nop 0
	v_mfma_f32_16x16x32_bf16 v[130:133], v[186:189], v[16:19], v[130:133]
	v_max3_f32 v80, v80, v116, v117
	v_mfma_f32_16x16x32_bf16 v[198:201], v[156:159], v[16:19], v[144:147]
	s_waitcnt lgkmcnt(0)
	v_mfma_f32_16x16x32_bf16 v[160:163], v[194:197], v[16:19], v[160:163]
	s_nop 3
	v_max3_f32 v80, v80, v130, v131
	v_max3_f32 v80, v80, v132, v133
	v_max3_f32 v80, v80, v198, v199
	v_max3_f32 v80, v80, v200, v201
	v_mfma_f32_16x16x32_bf16 v[202:205], v[110:113], v[8:11], 0
	v_max3_f32 v80, v80, v160, v161
	v_max3_f32 v80, v80, v162, v163
	v_mov_b32_e32 v126, v80
	v_mfma_f32_16x16x32_bf16 v[206:209], v[118:121], v[8:11], 0
	s_nop 0
	v_permlane16_swap_b32_e32 v126, v80
	v_max_f32_e32 v80, v80, v126
	v_mov_b32_e32 v126, v80
	v_mfma_f32_16x16x32_bf16 v[140:143], v[140:143], v[8:11], 0
	s_nop 0
	v_permlane32_swap_b32_e32 v126, v80
	v_mfma_f32_16x16x32_bf16 v[152:155], v[152:155], v[8:11], 0
	v_max_f32_e32 v80, v80, v126
	v_mul_f32_e32 v80, 0x3e16c740, v80
	v_mfma_f32_16x16x32_bf16 v[202:205], v[122:125], v[12:15], v[202:205]
	v_max_f32_e32 v146, v184, v80
	v_fma_f32 v110, v114, s37, -v146
	v_exp_f32_e32 v111, v110
	v_mfma_f32_16x16x32_bf16 v[164:167], v[164:167], v[12:15], v[206:209]
	v_fma_f32 v110, v115, s37, -v146
	v_exp_f32_e32 v113, v110
	v_fma_f32 v110, v116, s37, -v146
	v_mfma_f32_16x16x32_bf16 v[140:143], v[148:151], v[12:15], v[140:143]
	v_exp_f32_e32 v115, v110
	v_fma_f32 v110, v117, s37, -v146
	v_exp_f32_e32 v117, v110
	v_mfma_f32_16x16x32_bf16 v[148:151], v[190:193], v[12:15], v[152:155]
	v_fma_f32 v110, v130, s37, -v146
	v_exp_f32_e32 v119, v110
	v_fma_f32 v110, v131, s37, -v146
	v_mfma_f32_16x16x32_bf16 v[152:155], v[136:139], v[44:47], v[202:205]
	v_exp_f32_e32 v121, v110
	v_fma_f32 v110, v132, s37, -v146
	v_exp_f32_e32 v123, v110
	v_mfma_f32_16x16x32_bf16 v[164:167], v[186:189], v[44:47], v[164:167]
	v_fma_f32 v110, v133, s37, -v146
	s_nop 2
	v_max_f32_e32 v112, v152, v153
	s_nop 0
	s_nop 0
	v_mfma_f32_16x16x32_bf16 v[156:159], v[156:159], v[44:47], v[140:143]
	v_max3_f32 v112, v112, v154, v155
	v_max3_f32 v112, v112, v164, v165
	v_max3_f32 v112, v112, v166, v167
	v_mfma_f32_16x16x32_bf16 v[148:151], v[194:197], v[44:47], v[148:151]
	v_exp_f32_e32 v127, v110
	s_nop 2
	v_max3_f32 v112, v112, v156, v157
	v_max3_f32 v112, v112, v158, v159
	v_fma_f32 v110, v198, s37, -v146
	v_exp_f32_e32 v125, v110
	v_max3_f32 v112, v112, v148, v149
	v_max3_f32 v112, v112, v150, v151
	v_mov_b32_e32 v114, v112
	v_fma_f32 v110, v199, s37, -v146
	v_exp_f32_e32 v133, v110
	v_fma_f32 v110, v200, s37, -v146
	v_exp_f32_e32 v131, v110
	v_permlane16_swap_b32_e32 v114, v112
	v_max_f32_e32 v112, v112, v114
	v_fma_f32 v110, v201, s37, -v146
	v_mov_b32_e32 v114, v112
	v_exp_f32_e32 v135, v110
	v_fma_f32 v110, v160, s37, -v146
	v_exp_f32_e32 v137, v110
	v_fma_f32 v110, v161, s37, -v146
	v_exp_f32_e32 v139, v110
	v_fma_f32 v110, v162, s37, -v146
	v_exp_f32_e32 v141, v110
	v_fma_f32 v110, v163, s37, -v146
	v_exp_f32_e32 v143, v110
	v_permlane32_swap_b32_e32 v114, v112
	v_max_f32_e32 v110, v112, v114
	v_mul_f32_e32 v110, 0x3e16c740, v110
	v_max_f32_e32 v145, v97, v110
	v_sub_f32_e32 v80, v184, v146
	v_sub_f32_e32 v97, v97, v145
	v_fma_f32 v110, v152, s37, -v145
	v_fma_f32 v112, v153, s37, -v145
	v_fma_f32 v114, v154, s37, -v145
	v_fma_f32 v116, v155, s37, -v145
	v_fma_f32 v118, v164, s37, -v145
	v_fma_f32 v120, v165, s37, -v145
	v_fma_f32 v122, v166, s37, -v145
	v_fma_f32 v124, v167, s37, -v145
	v_exp_f32_e32 v80, v80
	v_exp_f32_e32 v110, v110
	v_exp_f32_e32 v112, v112
	v_exp_f32_e32 v114, v114
	v_exp_f32_e32 v116, v116
	v_exp_f32_e32 v118, v118
	v_exp_f32_e32 v120, v120
	v_exp_f32_e32 v122, v122
	v_exp_f32_e32 v126, v124
	v_fma_f32 v136, v148, s37, -v145
	v_fma_f32 v138, v149, s37, -v145
	v_fma_f32 v140, v150, s37, -v145
	v_fma_f32 v142, v151, s37, -v145
	v_exp_f32_e32 v144, v97
	ds_read_b64_tr_b16 v[150:151], v183 offset:15872
	ds_read_b64_tr_b16 v[148:149], v183 offset:13312
	ds_read_b64_tr_b16 v[160:161], v183 offset:13344
	ds_read_b64_tr_b16 v[164:165], v183 offset:13376
	ds_read_b64_tr_b16 v[184:185], v183 offset:13408
	ds_read_b64_tr_b16 v[162:163], v183 offset:15904
	ds_read_b64_tr_b16 v[166:167], v183 offset:15936
	ds_read_b64_tr_b16 v[186:187], v183 offset:15968
	v_fma_f32 v130, v157, s37, -v145
	v_cvt_pk_bf16_f32 v152, v111, v113
	v_cvt_pk_bf16_f32 v153, v115, v117
	v_cvt_pk_bf16_f32 v154, v119, v121
	v_cvt_pk_bf16_f32 v155, v123, v127
	v_fma_f32 v124, v156, s37, -v145
	v_exp_f32_e32 v132, v130
	v_fma_f32 v130, v158, s37, -v145
	v_fma_f32 v134, v159, s37, -v145
	v_pk_mul_f32 v[78:79], v[78:79], v[80:81] op_sel_hi:[1,0]
	v_pk_mul_f32 v[76:77], v[76:77], v[80:81] op_sel_hi:[1,0]
	v_pk_mul_f32 v[74:75], v[74:75], v[80:81] op_sel_hi:[1,0]
	v_pk_mul_f32 v[70:71], v[70:71], v[144:145] op_sel_hi:[1,0]
	v_pk_mul_f32 v[68:69], v[68:69], v[144:145] op_sel_hi:[1,0]
	v_cvt_pk_bf16_f32 v156, v110, v112
	v_cvt_pk_bf16_f32 v157, v114, v116
	v_cvt_pk_bf16_f32 v158, v118, v120
	v_cvt_pk_bf16_f32 v159, v122, v126
	v_pk_mul_f32 v[72:73], v[72:73], v[80:81] op_sel_hi:[1,0]
	v_pk_mul_f32 v[66:67], v[66:67], v[80:81] op_sel_hi:[1,0]
	v_pk_mul_f32 v[64:65], v[64:65], v[80:81] op_sel_hi:[1,0]
	v_pk_mul_f32 v[62:63], v[62:63], v[80:81] op_sel_hi:[1,0]
	v_pk_mul_f32 v[58:59], v[58:59], v[144:145] op_sel_hi:[1,0]
	v_pk_mul_f32 v[56:57], v[56:57], v[144:145] op_sel_hi:[1,0]
	v_pk_mul_f32 v[60:61], v[60:61], v[80:81] op_sel_hi:[1,0]
	v_pk_mul_f32 v[54:55], v[54:55], v[144:145] op_sel_hi:[1,0]
	v_pk_mul_f32 v[52:53], v[52:53], v[144:145] op_sel_hi:[1,0]
	v_pk_mul_f32 v[50:51], v[50:51], v[144:145] op_sel_hi:[1,0]
	v_pk_mul_f32 v[48:49], v[48:49], v[144:145] op_sel_hi:[1,0]
	v_exp_f32_e32 v124, v124
	v_exp_f32_e32 v130, v130
	v_exp_f32_e32 v134, v134
	v_exp_f32_e32 v136, v136
	v_exp_f32_e32 v138, v138
	v_exp_f32_e32 v140, v140
	v_exp_f32_e32 v142, v142
	s_waitcnt lgkmcnt(6)
	v_mfma_f32_16x16x32_bf16 v[76:79], v[148:151], v[152:155], v[76:79]
	v_mfma_f32_16x16x32_bf16 v[68:71], v[148:151], v[156:159], v[68:71]
	s_waitcnt lgkmcnt(2)
	v_mfma_f32_16x16x32_bf16 v[148:151], v[160:163], v[152:155], v[72:75]
	v_mfma_f32_16x16x32_bf16 v[56:59], v[160:163], v[156:159], v[56:59]
	v_cvt_pk_bf16_f32 v160, v125, v133
	v_cvt_pk_bf16_f32 v161, v131, v135
	v_cvt_pk_bf16_f32 v162, v137, v139
	s_waitcnt lgkmcnt(1)
	v_mfma_f32_16x16x32_bf16 v[64:67], v[164:167], v[152:155], v[64:67]
	v_cvt_pk_bf16_f32 v163, v141, v143
	v_mfma_f32_16x16x32_bf16 v[52:55], v[164:167], v[156:159], v[52:55]
	v_cvt_pk_bf16_f32 v164, v124, v132
	v_cvt_pk_bf16_f32 v165, v130, v134
	v_cvt_pk_bf16_f32 v166, v136, v138
	s_waitcnt lgkmcnt(0)
	v_mfma_f32_16x16x32_bf16 v[152:155], v[184:187], v[152:155], v[60:63]
	s_nop 2
	ds_read_b64_tr_b16 v[60:61], v183 offset:18432
	ds_read_b64_tr_b16 v[62:63], v183 offset:20992
	v_cvt_pk_bf16_f32 v167, v140, v142
	v_mfma_f32_16x16x32_bf16 v[156:159], v[184:187], v[156:159], v[48:51]
	s_nop 2
	ds_read_b64_tr_b16 v[48:49], v183 offset:18464
	ds_read_b64_tr_b16 v[184:185], v183 offset:18496
	ds_read_b64_tr_b16 v[188:189], v183 offset:18528
	ds_read_b64_tr_b16 v[50:51], v183 offset:21024
	ds_read_b64_tr_b16 v[186:187], v183 offset:21056
	ds_read_b64_tr_b16 v[190:191], v183 offset:21088
	s_waitcnt lgkmcnt(6)
	v_mfma_f32_16x16x32_bf16 v[76:79], v[60:63], v[160:163], v[76:79]
	v_mfma_f32_16x16x32_bf16 v[72:75], v[60:63], v[164:167], v[68:71]
	s_waitcnt lgkmcnt(2)
	v_mfma_f32_16x16x32_bf16 v[60:63], v[48:51], v[160:163], v[148:151]
	v_mfma_f32_16x16x32_bf16 v[56:59], v[48:51], v[164:167], v[56:59]
	s_waitcnt lgkmcnt(1)
	v_mfma_f32_16x16x32_bf16 v[64:67], v[184:187], v[160:163], v[64:67]
	v_mfma_f32_16x16x32_bf16 v[48:51], v[184:187], v[164:167], v[52:55]
	s_waitcnt lgkmcnt(0)
	v_mfma_f32_16x16x32_bf16 v[68:71], v[188:191], v[160:163], v[152:155]
	v_mfma_f32_16x16x32_bf16 v[52:55], v[188:191], v[164:167], v[156:159]
	s_cbranch_scc1 .LBB0_736
	v_add_u32_e32 v97, v87, v86
	s_waitcnt vmcnt(2)
	ds_write_b128 v97, v[20:23] offset:23552
	s_waitcnt vmcnt(1)
	ds_write_b128 v180, v[24:27] offset:36864
	s_and_saveexec_b64 s[28:29], s[4:5]
	s_cbranch_execz .LBB0_735
	s_waitcnt vmcnt(0)
	ds_write_b128 v181, v[32:35] offset:23680

.LBB0_738:
	s_waitcnt lgkmcnt(0)
	s_barrier
	ds_read_b128 v[148:151], v182 offset:23552
	ds_read_b128 v[162:165], v182 offset:33664
	ds_read_b128 v[156:159], v182 offset:26880
	ds_read_b128 v[192:195], v182 offset:26944
	s_waitcnt lgkmcnt(3)
	v_mfma_f32_16x16x32_bf16 v[152:155], v[148:151], v[0:3], 0
	ds_read_b128 v[196:199], v182 offset:30208
	ds_read_b128 v[200:203], v182 offset:27008
	ds_read_b128 v[208:211], v182 offset:33536
	ds_read_b128 v[212:215], v182 offset:33600
	ds_read_b128 v[220:223], v182 offset:23616
	ds_read_b128 v[224:227], v182 offset:23680
	s_waitcnt lgkmcnt(7)
	v_mfma_f32_16x16x32_bf16 v[186:189], v[156:159], v[0:3], 0
	ds_read_b128 v[228:231], v182 offset:30272
	ds_read_b128 v[232:235], v182 offset:30336
	s_add_i32 s39, s31, -2
	s_cmp_ge_u32 s39, s30
	s_waitcnt lgkmcnt(3)
	v_mfma_f32_16x16x32_bf16 v[152:155], v[220:223], v[4:7], v[152:155]
	v_mfma_f32_16x16x32_bf16 v[204:207], v[196:199], v[0:3], 0
	v_mfma_f32_16x16x32_bf16 v[216:219], v[208:211], v[0:3], 0
	v_mfma_f32_16x16x32_bf16 v[186:189], v[192:195], v[4:7], v[186:189]
	s_waitcnt lgkmcnt(2)
	v_mfma_f32_16x16x32_bf16 v[152:155], v[224:227], v[16:19], v[152:155]
	s_waitcnt lgkmcnt(1)
	v_mfma_f32_16x16x32_bf16 v[204:207], v[228:231], v[4:7], v[204:207]
	v_mfma_f32_16x16x32_bf16 v[216:219], v[212:215], v[4:7], v[216:219]
	s_nop 4
	v_max_f32_e32 v97, v152, v153
	s_nop 0
	s_nop 0
	v_mfma_f32_16x16x32_bf16 v[236:239], v[200:203], v[16:19], v[186:189]
	v_max3_f32 v97, v97, v154, v155
	s_waitcnt lgkmcnt(0)
	v_mfma_f32_16x16x32_bf16 v[204:207], v[232:235], v[16:19], v[204:207]
	v_mfma_f32_16x16x32_bf16 v[216:219], v[162:165], v[16:19], v[216:219]
	s_nop 3
	v_max3_f32 v97, v97, v236, v237
	v_max3_f32 v97, v97, v238, v239
	s_nop 0
	v_max3_f32 v97, v97, v204, v205
	v_max3_f32 v97, v97, v206, v207
	v_mfma_f32_16x16x32_bf16 v[148:151], v[148:151], v[8:11], 0
	v_max3_f32 v97, v97, v216, v217
	v_max3_f32 v97, v97, v218, v219
	v_mov_b32_e32 v147, v97
	v_mfma_f32_16x16x32_bf16 v[156:159], v[156:159], v[8:11], 0
	s_nop 0
	v_permlane16_swap_b32_e32 v147, v97
	v_max_f32_e32 v97, v97, v147
	v_mov_b32_e32 v147, v97
	v_mfma_f32_16x16x32_bf16 v[208:211], v[208:211], v[8:11], 0
	s_nop 0
	v_permlane32_swap_b32_e32 v147, v97
	v_max_f32_e32 v97, v97, v147
	v_mul_f32_e32 v97, 0x3e16c740, v97
	v_max_f32_e32 v184, v146, v97
	v_sub_f32_e32 v97, v146, v184
	v_fma_f32 v146, v152, s37, -v184
	v_exp_f32_e32 v186, v146
	v_fma_f32 v146, v153, s37, -v184
	v_exp_f32_e32 v187, v146
	v_fma_f32 v146, v154, s37, -v184
	v_exp_f32_e32 v188, v146
	v_fma_f32 v146, v155, s37, -v184
	v_exp_f32_e32 v189, v146
	v_fma_f32 v146, v236, s37, -v184
	v_exp_f32_e32 v190, v146
	v_fma_f32 v146, v237, s37, -v184
	v_exp_f32_e32 v191, v146
	v_fma_f32 v146, v238, s37, -v184
	v_exp_f32_e32 v147, v146
	v_fma_f32 v146, v239, s37, -v184
	v_mfma_f32_16x16x32_bf16 v[220:223], v[220:223], v[12:15], v[148:151]
	v_exp_f32_e32 v168, v97
	s_nop 0
	v_pk_mul_f32 v[78:79], v[78:79], v[168:169] op_sel_hi:[1,0]
	v_mfma_f32_16x16x32_bf16 v[196:199], v[196:199], v[8:11], 0
	v_exp_f32_e32 v151, v146
	v_fma_f32 v146, v204, s37, -v184
	v_exp_f32_e32 v149, v146
	v_fma_f32 v146, v205, s37, -v184
	v_mfma_f32_16x16x32_bf16 v[192:195], v[192:195], v[12:15], v[156:159]
	v_exp_f32_e32 v155, v146
	v_fma_f32 v146, v206, s37, -v184
	v_exp_f32_e32 v153, v146
	v_fma_f32 v146, v207, s37, -v184
	v_mfma_f32_16x16x32_bf16 v[204:207], v[212:215], v[12:15], v[208:211]
	v_exp_f32_e32 v159, v146
	v_fma_f32 v146, v216, s37, -v184
	v_exp_f32_e32 v157, v146
	v_mfma_f32_16x16x32_bf16 v[208:211], v[224:227], v[44:47], v[220:223]
	v_fma_f32 v146, v217, s37, -v184
	v_exp_f32_e32 v161, v146
	v_fma_f32 v150, v218, s37, -v184
	v_mfma_f32_16x16x32_bf16 v[196:199], v[228:231], v[12:15], v[196:199]
	v_cvt_pk_bf16_f32 v216, v186, v187
	s_nop 2
	v_max_f32_e32 v146, v208, v209
	s_nop 0
	v_mfma_f32_16x16x32_bf16 v[200:203], v[200:203], v[44:47], v[192:195]
	s_nop 0
	v_max3_f32 v146, v146, v210, v211
	v_cvt_pk_bf16_f32 v217, v188, v189
	v_mfma_f32_16x16x32_bf16 v[212:215], v[232:235], v[44:47], v[196:199]
	v_cvt_pk_bf16_f32 v218, v190, v191
	s_nop 2
	v_max3_f32 v146, v146, v200, v201
	v_max3_f32 v146, v146, v202, v203
	v_mfma_f32_16x16x32_bf16 v[204:207], v[162:165], v[44:47], v[204:207]
	v_exp_f32_e32 v163, v150
	v_max3_f32 v146, v146, v212, v213
	v_max3_f32 v146, v146, v214, v215
	v_fma_f32 v150, v219, s37, -v184
	v_exp_f32_e32 v165, v150
	s_nop 2
	v_max3_f32 v146, v146, v204, v205
	v_max3_f32 v146, v146, v206, v207
	v_mov_b32_e32 v148, v146
	v_pk_mul_f32 v[76:77], v[76:77], v[168:169] op_sel_hi:[1,0]
	v_pk_mul_f32 v[62:63], v[62:63], v[168:169] op_sel_hi:[1,0]
	v_cvt_pk_bf16_f32 v219, v147, v151
	v_pk_mul_f32 v[60:61], v[60:61], v[168:169] op_sel_hi:[1,0]
	v_permlane16_swap_b32_e32 v148, v146
	v_max_f32_e32 v146, v146, v148
	v_mov_b32_e32 v148, v146
	v_pk_mul_f32 v[66:67], v[66:67], v[168:169] op_sel_hi:[1,0]
	v_pk_mul_f32 v[64:65], v[64:65], v[168:169] op_sel_hi:[1,0]
	v_pk_mul_f32 v[70:71], v[70:71], v[168:169] op_sel_hi:[1,0]
	v_pk_mul_f32 v[68:69], v[68:69], v[168:169] op_sel_hi:[1,0]
	v_permlane32_swap_b32_e32 v148, v146
	v_max_f32_e32 v97, v146, v148
	v_mul_f32_e32 v97, 0x3e16c740, v97
	v_max_f32_e32 v97, v145, v97
	v_fma_f32 v146, v208, s37, -v97
	v_exp_f32_e32 v192, v146
	v_fma_f32 v146, v209, s37, -v97
	v_exp_f32_e32 v193, v146
	v_fma_f32 v146, v210, s37, -v97
	v_exp_f32_e32 v194, v146
	v_fma_f32 v146, v211, s37, -v97
	v_exp_f32_e32 v195, v146
	v_fma_f32 v146, v200, s37, -v97
	v_exp_f32_e32 v196, v146
	v_fma_f32 v146, v201, s37, -v97
	v_sub_f32_e32 v145, v145, v97
	v_exp_f32_e32 v197, v146
	v_fma_f32 v146, v202, s37, -v97
	v_fma_f32 v148, v203, s37, -v97
	v_exp_f32_e32 v146, v146
	v_exp_f32_e32 v150, v148
	v_fma_f32 v148, v212, s37, -v97
	v_fma_f32 v152, v213, s37, -v97
	v_fma_f32 v162, v206, s37, -v97
	v_fma_f32 v164, v207, s37, -v97
	v_exp_f32_e32 v166, v145
	ds_read_b64_tr_b16 v[200:201], v183 offset:39424
	ds_read_b64_tr_b16 v[198:199], v183 offset:36864
	ds_read_b64_tr_b16 v[206:207], v183 offset:36896
	ds_read_b64_tr_b16 v[210:211], v183 offset:36928
	ds_read_b64_tr_b16 v[220:221], v183 offset:36960
	ds_read_b64_tr_b16 v[208:209], v183 offset:39456
	ds_read_b64_tr_b16 v[212:213], v183 offset:39488
	ds_read_b64_tr_b16 v[222:223], v183 offset:39520
	v_fma_f32 v156, v215, s37, -v97
	v_exp_f32_e32 v154, v152
	v_fma_f32 v152, v214, s37, -v97
	v_exp_f32_e32 v158, v156
	v_fma_f32 v156, v204, s37, -v97
	v_fma_f32 v160, v205, s37, -v97
	v_pk_mul_f32 v[74:75], v[74:75], v[166:167] op_sel_hi:[1,0]
	v_pk_mul_f32 v[72:73], v[72:73], v[166:167] op_sel_hi:[1,0]
	v_cvt_pk_bf16_f32 v202, v192, v193
	v_cvt_pk_bf16_f32 v203, v194, v195
	v_cvt_pk_bf16_f32 v204, v196, v197
	v_cvt_pk_bf16_f32 v205, v146, v150
	v_pk_mul_f32 v[58:59], v[58:59], v[166:167] op_sel_hi:[1,0]
	v_pk_mul_f32 v[56:57], v[56:57], v[166:167] op_sel_hi:[1,0]
	v_pk_mul_f32 v[50:51], v[50:51], v[166:167] op_sel_hi:[1,0]
	v_pk_mul_f32 v[48:49], v[48:49], v[166:167] op_sel_hi:[1,0]
	v_pk_mul_f32 v[54:55], v[54:55], v[166:167] op_sel_hi:[1,0]
	v_pk_mul_f32 v[52:53], v[52:53], v[166:167] op_sel_hi:[1,0]
	v_exp_f32_e32 v148, v148
	v_exp_f32_e32 v152, v152
	v_exp_f32_e32 v156, v156
	v_exp_f32_e32 v160, v160
	v_exp_f32_e32 v162, v162
	v_exp_f32_e32 v164, v164
	s_waitcnt lgkmcnt(6)
	v_mfma_f32_16x16x32_bf16 v[76:79], v[198:201], v[216:219], v[76:79]
	v_mfma_f32_16x16x32_bf16 v[72:75], v[198:201], v[202:205], v[72:75]
	v_cvt_pk_bf16_f32 v198, v149, v155
	v_cvt_pk_bf16_f32 v199, v153, v159
	v_cvt_pk_bf16_f32 v200, v157, v161
	s_waitcnt lgkmcnt(2)
	v_mfma_f32_16x16x32_bf16 v[60:63], v[206:209], v[216:219], v[60:63]
	v_cvt_pk_bf16_f32 v201, v163, v165
	v_mfma_f32_16x16x32_bf16 v[56:59], v[206:209], v[202:205], v[56:59]
	s_waitcnt lgkmcnt(1)
	v_mfma_f32_16x16x32_bf16 v[64:67], v[210:213], v[216:219], v[64:67]
	v_mfma_f32_16x16x32_bf16 v[48:51], v[210:213], v[202:205], v[48:51]
	v_cvt_pk_bf16_f32 v210, v148, v154
	v_cvt_pk_bf16_f32 v211, v152, v158
	v_cvt_pk_bf16_f32 v212, v156, v160
	s_waitcnt lgkmcnt(0)
	v_mfma_f32_16x16x32_bf16 v[206:209], v[220:223], v[216:219], v[68:71]
	s_nop 2
	ds_read_b64_tr_b16 v[68:69], v183 offset:41984
	ds_read_b64_tr_b16 v[70:71], v183 offset:44544
	v_cvt_pk_bf16_f32 v213, v162, v164
	v_mfma_f32_16x16x32_bf16 v[202:205], v[220:223], v[202:205], v[52:55]
	s_nop 2
	ds_read_b64_tr_b16 v[52:53], v183 offset:42016
	ds_read_b64_tr_b16 v[214:215], v183 offset:42048
	ds_read_b64_tr_b16 v[218:219], v183 offset:42080
	ds_read_b64_tr_b16 v[54:55], v183 offset:44576
	ds_read_b64_tr_b16 v[216:217], v183 offset:44608
	ds_read_b64_tr_b16 v[220:221], v183 offset:44640
	s_waitcnt lgkmcnt(6)
	v_mfma_f32_16x16x32_bf16 v[76:79], v[68:71], v[198:201], v[76:79]
	v_mfma_f32_16x16x32_bf16 v[68:71], v[68:71], v[210:213], v[72:75]
	s_waitcnt lgkmcnt(2)
	v_mfma_f32_16x16x32_bf16 v[72:75], v[52:55], v[198:201], v[60:63]
	v_mfma_f32_16x16x32_bf16 v[56:59], v[52:55], v[210:213], v[56:59]
	s_waitcnt lgkmcnt(1)
	v_mfma_f32_16x16x32_bf16 v[64:67], v[214:217], v[198:201], v[64:67]
	v_mfma_f32_16x16x32_bf16 v[52:55], v[214:217], v[210:213], v[48:51]
	s_waitcnt lgkmcnt(0)
	v_mfma_f32_16x16x32_bf16 v[60:63], v[218:221], v[198:201], v[206:209]
	v_mfma_f32_16x16x32_bf16 v[48:51], v[218:221], v[210:213], v[202:205]
	s_cbranch_scc1 .LBB0_742
	s_waitcnt vmcnt(2)
	ds_write_b128 v178, v[28:31]
	s_waitcnt vmcnt(1)
	ds_write_b128 v179, v[36:39] offset:13312
	s_and_saveexec_b64 s[28:29], s[4:5]
	s_cbranch_execz .LBB0_741
	s_waitcnt vmcnt(0)
	ds_write_b128 v181, v[40:43] offset:128
